# speedup vs baseline: 1.0039x; 1.0022x over previous
; template <int NT, int BM, int BN, bool PLAIN, int NSTAGE, bool EPI_LDS>
; __device__ __forceinline__ void gemm_tile(const Params& p, const GemmDesc& g, bf16_t* lds, const int tid) {
;     ...
;       for (; kt + 2 < nk; ++kt) {
;         const int cur = kt & 1;
;         COMPUTE_X(cur, 1, 1, kt + 2)
;         __syncthreads();
;       }
.LBB0_897:
	s_and_b32 s28, s26, 0x10000
	s_xor_b32 s29, s28, 0x10000
	s_add_u32 m0, s29, s57
	s_add_u32 m0, m0, 0x1000
	v_or_b32_e32 v0, s28, v180
	v_add_u32_e32 v218, v0, v184
	v_add_u32_e32 v0, v0, v183
	s_waitcnt lgkmcnt(2)
	v_mfma_f32_16x16x32_bf16 v[158:161], v[2:5], v[202:205], v[158:161]
	global_load_lds_dwordx4 v166, s[60:61]
	s_add_u32 m0, m0, 0x400
	v_add_u32_e32 v218, v218, v181
	s_add_i32 s27, s27, -1
	v_mfma_f32_16x16x32_bf16 v[154:157], v[6:9], v[202:205], v[154:157]
	s_add_i32 s26, s26, 0x10000
	v_mfma_f32_16x16x32_bf16 v[150:153], v[10:13], v[202:205], v[150:153]
	global_load_lds_dwordx4 v167, s[60:61]
	s_add_u32 m0, m0, 0x400
	v_mfma_f32_16x16x32_bf16 v[146:149], v[14:17], v[202:205], v[146:149]
	ds_read_b128 v[202:205], v0 offset:6144
	s_waitcnt lgkmcnt(2)
	v_mfma_f32_16x16x32_bf16 v[142:145], v[2:5], v[206:209], v[142:145]
	global_load_lds_dwordx4 v168, s[60:61]
	s_add_u32 m0, m0, 0x400
	v_mfma_f32_16x16x32_bf16 v[138:141], v[6:9], v[206:209], v[138:141]
	v_mfma_f32_16x16x32_bf16 v[134:137], v[10:13], v[206:209], v[134:137]
	global_load_lds_dwordx4 v169, s[60:61]
	s_add_u32 s60, s60, 0x80
	s_addc_u32 s61, s61, 0
	v_mfma_f32_16x16x32_bf16 v[130:133], v[14:17], v[206:209], v[130:133]
	ds_read_b128 v[206:209], v0 offset:8192
	s_waitcnt lgkmcnt(2)
	v_mfma_f32_16x16x32_bf16 v[126:129], v[2:5], v[226:229], v[126:129]
	v_mfma_f32_16x16x32_bf16 v[122:125], v[6:9], v[226:229], v[122:125]
	v_mfma_f32_16x16x32_bf16 v[118:121], v[10:13], v[226:229], v[118:121]
	v_mfma_f32_16x16x32_bf16 v[114:117], v[14:17], v[226:229], v[114:117]
	ds_read_b128 v[226:229], v0 offset:10240
	s_waitcnt lgkmcnt(2)
	v_mfma_f32_16x16x32_bf16 v[106:109], v[2:5], v[202:205], v[106:109]
	v_mfma_f32_16x16x32_bf16 v[102:105], v[6:9], v[202:205], v[102:105]
	v_mfma_f32_16x16x32_bf16 v[98:101], v[10:13], v[202:205], v[98:101]
	v_mfma_f32_16x16x32_bf16 v[94:97], v[14:17], v[202:205], v[94:97]
	ds_read_b128 v[202:205], v0 offset:12288
	ds_read_b128 v[230:233], v218 offset:32768
	s_waitcnt lgkmcnt(3)
	v_mfma_f32_16x16x32_bf16 v[86:89], v[2:5], v[206:209], v[86:89]
	v_mfma_f32_16x16x32_bf16 v[82:85], v[6:9], v[206:209], v[82:85]
	v_mfma_f32_16x16x32_bf16 v[78:81], v[10:13], v[206:209], v[78:81]
	v_mfma_f32_16x16x32_bf16 v[74:77], v[14:17], v[206:209], v[74:77]
	ds_read_b128 v[206:209], v0 offset:14336
	ds_read_b128 v[234:237], v218 offset:34816
	v_add_u32_e32 v0, v0, v181
	s_waitcnt lgkmcnt(4)
	v_mfma_f32_16x16x32_bf16 v[70:73], v[2:5], v[226:229], v[70:73]
	v_mfma_f32_16x16x32_bf16 v[66:69], v[6:9], v[226:229], v[66:69]
	v_mfma_f32_16x16x32_bf16 v[62:65], v[10:13], v[226:229], v[62:65]
	v_mfma_f32_16x16x32_bf16 v[58:61], v[14:17], v[226:229], v[58:61]
	ds_read_b128 v[226:229], v0 offset:0
	ds_read_b128 v[238:241], v218 offset:36864
	s_waitcnt lgkmcnt(5)
	v_mfma_f32_16x16x32_bf16 v[54:57], v[2:5], v[202:205], v[54:57]
	v_mfma_f32_16x16x32_bf16 v[50:53], v[6:9], v[202:205], v[50:53]
	v_mfma_f32_16x16x32_bf16 v[46:49], v[10:13], v[202:205], v[46:49]
	v_mfma_f32_16x16x32_bf16 v[42:45], v[14:17], v[202:205], v[42:45]
	ds_read_b128 v[202:205], v0 offset:2048
	ds_read_b128 v[242:245], v218 offset:38912
	s_waitcnt lgkmcnt(5)
	v_mfma_f32_16x16x32_bf16 v[38:41], v[2:5], v[206:209], v[38:41]
	v_mfma_f32_16x16x32_bf16 v[34:37], v[6:9], v[206:209], v[34:37]
	v_mfma_f32_16x16x32_bf16 v[90:93], v[10:13], v[206:209], v[90:93]
	v_mfma_f32_16x16x32_bf16 v[110:113], v[14:17], v[206:209], v[110:113]
	ds_read_b128 v[186:189], v0 offset:4096
	s_waitcnt lgkmcnt(4)
	v_mfma_f32_16x16x32_bf16 v[158:161], v[230:233], v[226:229], v[158:161]
	v_mfma_f32_16x16x32_bf16 v[154:157], v[234:237], v[226:229], v[154:157]
	s_waitcnt lgkmcnt(3)
	v_mfma_f32_16x16x32_bf16 v[150:153], v[238:241], v[226:229], v[150:153]
	s_waitcnt lgkmcnt(1)
	v_mfma_f32_16x16x32_bf16 v[146:149], v[242:245], v[226:229], v[146:149]
	ds_read_b128 v[190:193], v0 offset:6144
	v_mfma_f32_16x16x32_bf16 v[142:145], v[230:233], v[202:205], v[142:145]
	v_mfma_f32_16x16x32_bf16 v[138:141], v[234:237], v[202:205], v[138:141]
	v_mfma_f32_16x16x32_bf16 v[134:137], v[238:241], v[202:205], v[134:137]
	v_mfma_f32_16x16x32_bf16 v[130:133], v[242:245], v[202:205], v[130:133]
	ds_read_b128 v[194:197], v0 offset:8192
	s_waitcnt lgkmcnt(2)
	v_mfma_f32_16x16x32_bf16 v[126:129], v[230:233], v[186:189], v[126:129]
	v_mfma_f32_16x16x32_bf16 v[122:125], v[234:237], v[186:189], v[122:125]
	v_mfma_f32_16x16x32_bf16 v[118:121], v[238:241], v[186:189], v[118:121]
	v_mfma_f32_16x16x32_bf16 v[114:117], v[242:245], v[186:189], v[114:117]
	ds_read_b128 v[186:189], v0 offset:10240
	s_waitcnt lgkmcnt(2)
	v_mfma_f32_16x16x32_bf16 v[106:109], v[230:233], v[190:193], v[106:109]
	v_mfma_f32_16x16x32_bf16 v[102:105], v[234:237], v[190:193], v[102:105]
	v_mfma_f32_16x16x32_bf16 v[98:101], v[238:241], v[190:193], v[98:101]
	v_mfma_f32_16x16x32_bf16 v[94:97], v[242:245], v[190:193], v[94:97]
	ds_read_b128 v[190:193], v0 offset:12288
	s_waitcnt lgkmcnt(2)
	v_mfma_f32_16x16x32_bf16 v[86:89], v[230:233], v[194:197], v[86:89]
	v_mfma_f32_16x16x32_bf16 v[82:85], v[234:237], v[194:197], v[82:85]
	v_mfma_f32_16x16x32_bf16 v[78:81], v[238:241], v[194:197], v[78:81]
	v_mfma_f32_16x16x32_bf16 v[74:77], v[242:245], v[194:197], v[74:77]
	ds_read_b128 v[194:197], v0 offset:14336
	s_waitcnt lgkmcnt(2)
	v_mfma_f32_16x16x32_bf16 v[70:73], v[230:233], v[186:189], v[70:73]
	v_mfma_f32_16x16x32_bf16 v[66:69], v[234:237], v[186:189], v[66:69]
	v_mfma_f32_16x16x32_bf16 v[62:65], v[238:241], v[186:189], v[62:65]
	v_mfma_f32_16x16x32_bf16 v[58:61], v[242:245], v[186:189], v[58:61]
	s_waitcnt vmcnt(0) lgkmcnt(0)
	s_barrier
; template <int NT, int BM, int BN, bool PLAIN, int NSTAGE, bool EPI_LDS>
; __device__ __forceinline__ void gemm_tile(const Params& p, const GemmDesc& g, bf16_t* lds, const int tid) {
;     ...
;     if (PLAIN) {
;       int kt = 0;
;       for (; kt + 2 < nk; ++kt) {
;         const int cur = kt & 1;
;         COMPUTE_X(cur, 1, 1, kt + 2)
;         __syncthreads();
;       }
;       if (kt + 1 < nk) {
;         const int cur = kt & 1;
;         COMPUTE_X(cur, 1, 0, 0)
;         __syncthreads();
;         ++kt;
	s_xor_b32 s29, s28, 0x10000
	v_or_b32_e32 v18, s29, v180
	v_add_u32_e32 v19, v18, v184
	v_add_u32_e32 v18, v18, v183
	ds_read_b128 v[2:5], v19 offset:32768
	ds_read_b128 v[6:9], v19 offset:34816
	ds_read_b128 v[10:13], v19 offset:36864
	ds_read_b128 v[14:17], v19 offset:38912
	ds_read_b128 v[202:205], v18
	ds_read_b128 v[206:209], v18 offset:2048
	ds_read_b128 v[226:229], v18 offset:4096
	s_add_u32 m0, s28, s57
	v_mfma_f32_16x16x32_bf16 v[54:57], v[230:233], v[190:193], v[54:57]
	global_load_lds_dwordx4 v162, s[60:61]
	s_add_u32 m0, m0, 0x400
	v_mfma_f32_16x16x32_bf16 v[50:53], v[234:237], v[190:193], v[50:53]
	v_mfma_f32_16x16x32_bf16 v[46:49], v[238:241], v[190:193], v[46:49]
	global_load_lds_dwordx4 v163, s[60:61]
	s_add_u32 m0, m0, 0x400
	v_mfma_f32_16x16x32_bf16 v[42:45], v[242:245], v[190:193], v[42:45]
	v_mfma_f32_16x16x32_bf16 v[38:41], v[230:233], v[194:197], v[38:41]
	global_load_lds_dwordx4 v164, s[60:61]
	s_add_u32 m0, m0, 0x400
	v_mfma_f32_16x16x32_bf16 v[34:37], v[234:237], v[194:197], v[34:37]
	v_mfma_f32_16x16x32_bf16 v[90:93], v[238:241], v[194:197], v[90:93]
	global_load_lds_dwordx4 v165, s[60:61]
	v_mfma_f32_16x16x32_bf16 v[110:113], v[242:245], v[194:197], v[110:113]
	s_cmp_lg_u32 s27, 0
	s_cbranch_scc1 .LBB0_897
	s_lshl_b32 s3, s3, 16
	s_and_b32 s3, s3, 0x10000
	s_xor_b32 s29, s3, 0x10000
	s_add_u32 m0, s29, s57
	s_add_u32 m0, m0, 0x1000
	s_nop 0
	global_load_lds_dwordx4 v166, s[60:61]
	s_add_u32 m0, m0, 0x400
	s_nop 0
	global_load_lds_dwordx4 v167, s[60:61]
	s_add_u32 m0, m0, 0x400
	s_nop 0
	global_load_lds_dwordx4 v168, s[60:61]
	s_add_u32 m0, m0, 0x400
	s_nop 0
	global_load_lds_dwordx4 v169, s[60:61]
	v_or_b32_e32 v0, s3, v180
	v_add_u32_e32 v198, v0, v184
	ds_read_b128 v[162:165], v198 offset:32768
	ds_read_b128 v[166:169], v198 offset:34816
	ds_read_b128 v[170:173], v198 offset:36864
	ds_read_b128 v[186:189], v198 offset:38912
	v_add_u32_e32 v0, v0, v183
	ds_read_b128 v[174:177], v0
	ds_read_b128 v[190:193], v0 offset:2048
	ds_read_b128 v[194:197], v0 offset:4096
	s_waitcnt lgkmcnt(2)
	v_mfma_f32_16x16x32_bf16 v[30:33], v[162:165], v[174:177], v[158:161]
	s_not_b32 s3, s23
	s_lshl_b32 s3, s3, 16
	s_and_b32 s3, s3, 0x10000
	v_mfma_f32_16x16x32_bf16 v[154:157], v[166:169], v[174:177], v[154:157]
	s_cmp_lg_u32 s56, 9
	s_cselect_b64 s[26:27], -1, 0
	s_mov_b32 s24, s41
	v_mfma_f32_16x16x32_bf16 v[150:153], v[170:173], v[174:177], v[150:153]
	s_mov_b32 s23, s42
	s_mov_b64 s[28:29], -1
	s_and_b64 vcc, exec, s[26:27]
	v_mfma_f32_16x16x32_bf16 v[146:149], v[186:189], v[174:177], v[146:149]
	ds_read_b128 v[158:161], v0 offset:6144
	v_add_u32_e32 v174, v198, v181
	s_waitcnt lgkmcnt(2)
	v_mfma_f32_16x16x32_bf16 v[26:29], v[162:165], v[190:193], v[142:145]
	v_mfma_f32_16x16x32_bf16 v[138:141], v[166:169], v[190:193], v[138:141]
	v_mfma_f32_16x16x32_bf16 v[134:137], v[170:173], v[190:193], v[134:137]
	v_mfma_f32_16x16x32_bf16 v[130:133], v[186:189], v[190:193], v[130:133]
	ds_read_b128 v[142:145], v0 offset:8192
	s_waitcnt lgkmcnt(2)
	v_mfma_f32_16x16x32_bf16 v[22:25], v[162:165], v[194:197], v[126:129]
	v_mfma_f32_16x16x32_bf16 v[122:125], v[166:169], v[194:197], v[122:125]
	v_mfma_f32_16x16x32_bf16 v[118:121], v[170:173], v[194:197], v[118:121]
	v_mfma_f32_16x16x32_bf16 v[114:117], v[186:189], v[194:197], v[114:117]
	ds_read_b128 v[126:129], v0 offset:10240
	s_waitcnt lgkmcnt(2)
	v_mfma_f32_16x16x32_bf16 v[18:21], v[162:165], v[158:161], v[106:109]
	v_mfma_f32_16x16x32_bf16 v[102:105], v[166:169], v[158:161], v[102:105]
	v_mfma_f32_16x16x32_bf16 v[98:101], v[170:173], v[158:161], v[98:101]
	v_mfma_f32_16x16x32_bf16 v[94:97], v[186:189], v[158:161], v[94:97]
	ds_read_b128 v[106:109], v0 offset:12288
	ds_read_b128 v[158:161], v174 offset:32768
	s_waitcnt lgkmcnt(3)
	v_mfma_f32_16x16x32_bf16 v[14:17], v[162:165], v[142:145], v[86:89]
	v_mfma_f32_16x16x32_bf16 v[82:85], v[166:169], v[142:145], v[82:85]
	v_mfma_f32_16x16x32_bf16 v[78:81], v[170:173], v[142:145], v[78:81]
	v_mfma_f32_16x16x32_bf16 v[74:77], v[186:189], v[142:145], v[74:77]
	ds_read_b128 v[86:89], v0 offset:14336
	ds_read_b128 v[142:145], v174 offset:34816
	v_add_u32_e32 v0, v0, v181
	s_waitcnt lgkmcnt(4)
	v_mfma_f32_16x16x32_bf16 v[10:13], v[162:165], v[126:129], v[70:73]
	v_mfma_f32_16x16x32_bf16 v[66:69], v[166:169], v[126:129], v[66:69]
	v_mfma_f32_16x16x32_bf16 v[62:65], v[170:173], v[126:129], v[62:65]
	v_mfma_f32_16x16x32_bf16 v[58:61], v[186:189], v[126:129], v[58:61]
	ds_read_b128 v[70:73], v0 offset:0
	ds_read_b128 v[126:129], v174 offset:36864
	s_waitcnt lgkmcnt(5)
	v_mfma_f32_16x16x32_bf16 v[6:9], v[162:165], v[106:109], v[54:57]
	v_mfma_f32_16x16x32_bf16 v[50:53], v[166:169], v[106:109], v[50:53]
	v_mfma_f32_16x16x32_bf16 v[46:49], v[170:173], v[106:109], v[46:49]
	v_mfma_f32_16x16x32_bf16 v[42:45], v[186:189], v[106:109], v[42:45]
	ds_read_b128 v[106:109], v174 offset:38912
	ds_read_b128 v[54:57], v0 offset:2048
	s_waitcnt lgkmcnt(5)
	v_mfma_f32_16x16x32_bf16 v[2:5], v[162:165], v[86:89], v[38:41]
	v_mfma_f32_16x16x32_bf16 v[34:37], v[166:169], v[86:89], v[34:37]
	v_mfma_f32_16x16x32_bf16 v[38:41], v[170:173], v[86:89], v[90:93]
	v_mfma_f32_16x16x32_bf16 v[86:89], v[186:189], v[86:89], v[110:113]
	s_nop 1
	ds_read_b128 v[90:93], v0 offset:4096
	s_waitcnt lgkmcnt(4)
	v_mfma_f32_16x16x32_bf16 v[30:33], v[158:161], v[70:73], v[30:33]
	v_mfma_f32_16x16x32_bf16 v[110:113], v[142:145], v[70:73], v[154:157]
	s_waitcnt lgkmcnt(3)
	v_mfma_f32_16x16x32_bf16 v[150:153], v[126:129], v[70:73], v[150:153]
	s_waitcnt lgkmcnt(2)
	v_mfma_f32_16x16x32_bf16 v[70:73], v[106:109], v[70:73], v[146:149]
	s_nop 2
	ds_read_b128 v[146:149], v0 offset:6144
	s_waitcnt lgkmcnt(2)
; template <int NT, int BM, int BN, bool PLAIN, int NSTAGE, bool EPI_LDS>
; __device__ __forceinline__ void gemm_tile(const Params& p, const GemmDesc& g, bf16_t* lds, const int tid) {
;     ...
;       if (kt + 1 < nk) {
;         const int cur = kt & 1;
;         COMPUTE_X(cur, 1, 0, 0)
;         __syncthreads();
;         ++kt;
;       }
	v_mfma_f32_16x16x32_bf16 v[26:29], v[158:161], v[54:57], v[26:29]
	v_mfma_f32_16x16x32_bf16 v[138:141], v[142:145], v[54:57], v[138:141]
	v_mfma_f32_16x16x32_bf16 v[134:137], v[126:129], v[54:57], v[134:137]
	v_mfma_f32_16x16x32_bf16 v[54:57], v[106:109], v[54:57], v[130:133]
	s_nop 2
	ds_read_b128 v[130:133], v0 offset:8192
	s_waitcnt lgkmcnt(2)
	v_mfma_f32_16x16x32_bf16 v[22:25], v[158:161], v[90:93], v[22:25]
	v_mfma_f32_16x16x32_bf16 v[122:125], v[142:145], v[90:93], v[122:125]
	v_mfma_f32_16x16x32_bf16 v[118:121], v[126:129], v[90:93], v[118:121]
	v_mfma_f32_16x16x32_bf16 v[90:93], v[106:109], v[90:93], v[114:117]
	s_nop 2
	ds_read_b128 v[114:117], v0 offset:10240
	s_waitcnt lgkmcnt(2)
	v_mfma_f32_16x16x32_bf16 v[18:21], v[158:161], v[146:149], v[18:21]
	v_mfma_f32_16x16x32_bf16 v[102:105], v[142:145], v[146:149], v[102:105]
	v_mfma_f32_16x16x32_bf16 v[98:101], v[126:129], v[146:149], v[98:101]
	v_mfma_f32_16x16x32_bf16 v[94:97], v[106:109], v[146:149], v[94:97]
	ds_read_b128 v[146:149], v0 offset:12288
	s_waitcnt lgkmcnt(2)
	v_mfma_f32_16x16x32_bf16 v[14:17], v[158:161], v[130:133], v[14:17]
	v_mfma_f32_16x16x32_bf16 v[82:85], v[142:145], v[130:133], v[82:85]
	v_mfma_f32_16x16x32_bf16 v[78:81], v[126:129], v[130:133], v[78:81]
	v_mfma_f32_16x16x32_bf16 v[74:77], v[106:109], v[130:133], v[74:77]
	ds_read_b128 v[130:133], v0 offset:14336
	v_or_b32_e32 v0, s3, v180
	v_add_u32_e32 v186, v0, v184
	s_waitcnt lgkmcnt(2)
	v_mfma_f32_16x16x32_bf16 v[10:13], v[158:161], v[114:117], v[10:13]
	s_waitcnt vmcnt(0) lgkmcnt(0)
	s_barrier
; template <int NT, int BM, int BN, bool PLAIN, int NSTAGE, bool EPI_LDS>
; __device__ __forceinline__ void gemm_tile(const Params& p, const GemmDesc& g, bf16_t* lds, const int tid) {
;     ...
;       {
;         const int cur = kt & 1;
;         COMPUTE_X(cur, 0, 0, 0)
;         __syncthreads();
;       }
;     } else {
;       for (int kt = 0; kt < nk; ++kt) {
;         const int cur = kt & 1;
;         if (kt + 1 < nk) {
;           LWRITE(cur ^ 1)
;           if (kt + 2 < nk) GLOAD(kt + 2)
;         }
;         __builtin_amdgcn_sched_barrier(0);
;         COMPUTE(cur)
;         __syncthreads();
;       }
;     }
;   }
;     ...
;   int m0e = m0, n0e = n0;
;   asm volatile("" : "+s"(m0e), "+s"(n0e));
;   if (EPI_LDS) {
;     constexpr int CST = BN + 16;
;     bf16_t* ct = lds;
;     const bool relu2 = (g.epi == E_RELU2);
; #pragma unroll
;     for (int mi = 0; mi < MI; ++mi)
; #pragma unroll
;       for (int ni = 0; ni < NI; ++ni) {
;         f32x4 v = acc[mi][ni];
;         if (relu2) {
; #pragma unroll
;           for (int j = 0; j < 4; ++j) { const float r = fmaxf(v[j], 0.f); v[j] = r * r; }
;         }
;         u32x2 w;
;         w[0] = pack2(v[0], v[1]);
;         w[1] = pack2(v[2], v[3]);
;         *(u32x2*)(ct + (wm * WTM + mi * 16 + fr) * CST + wn * WTN + ni * 16 + fq * 4) = w;
	v_mfma_f32_16x16x32_bf16 v[66:69], v[142:145], v[114:117], v[66:69]
	v_add_u32_e32 v0, v0, v183
	v_mfma_f32_16x16x32_bf16 v[62:65], v[126:129], v[114:117], v[62:65]
	v_mfma_f32_16x16x32_bf16 v[58:61], v[106:109], v[114:117], v[58:61]
	v_mfma_f32_16x16x32_bf16 v[6:9], v[158:161], v[146:149], v[6:9]
	v_mfma_f32_16x16x32_bf16 v[50:53], v[142:145], v[146:149], v[50:53]
	v_mfma_f32_16x16x32_bf16 v[46:49], v[126:129], v[146:149], v[46:49]
	v_mfma_f32_16x16x32_bf16 v[42:45], v[106:109], v[146:149], v[42:45]
	v_mfma_f32_16x16x32_bf16 v[2:5], v[158:161], v[130:133], v[2:5]
	v_mfma_f32_16x16x32_bf16 v[34:37], v[142:145], v[130:133], v[34:37]
	v_mfma_f32_16x16x32_bf16 v[38:41], v[126:129], v[130:133], v[38:41]
	v_mfma_f32_16x16x32_bf16 v[86:89], v[106:109], v[130:133], v[86:89]
	ds_read_b128 v[106:109], v186 offset:32768
	ds_read_b128 v[114:117], v186 offset:34816
	ds_read_b128 v[130:133], v186 offset:36864
	ds_read_b128 v[142:145], v186 offset:38912
	ds_read_b128 v[126:129], v0
	ds_read_b128 v[146:149], v0 offset:2048
	ds_read_b128 v[154:157], v0 offset:4096
	s_waitcnt lgkmcnt(2)
	v_mfma_f32_16x16x32_bf16 v[30:33], v[106:109], v[126:129], v[30:33]
	v_mfma_f32_16x16x32_bf16 v[110:113], v[114:117], v[126:129], v[110:113]
	v_mfma_f32_16x16x32_bf16 v[150:153], v[130:133], v[126:129], v[150:153]
	v_mfma_f32_16x16x32_bf16 v[70:73], v[142:145], v[126:129], v[70:73]
	ds_read_b128 v[126:129], v0 offset:6144
	s_waitcnt lgkmcnt(2)
	v_mfma_f32_16x16x32_bf16 v[26:29], v[106:109], v[146:149], v[26:29]
	v_mfma_f32_16x16x32_bf16 v[138:141], v[114:117], v[146:149], v[138:141]
	v_mfma_f32_16x16x32_bf16 v[134:137], v[130:133], v[146:149], v[134:137]
	v_mfma_f32_16x16x32_bf16 v[54:57], v[142:145], v[146:149], v[54:57]
	ds_read_b128 v[146:149], v0 offset:8192
	s_waitcnt lgkmcnt(2)
	v_mfma_f32_16x16x32_bf16 v[22:25], v[106:109], v[154:157], v[22:25]
	v_mfma_f32_16x16x32_bf16 v[158:161], v[114:117], v[154:157], v[122:125]
	v_mfma_f32_16x16x32_bf16 v[162:165], v[130:133], v[154:157], v[118:121]
	v_mfma_f32_16x16x32_bf16 v[154:157], v[142:145], v[154:157], v[90:93]
	s_nop 2
	ds_read_b128 v[90:93], v0 offset:10240
	s_waitcnt lgkmcnt(2)
	v_mfma_f32_16x16x32_bf16 v[18:21], v[106:109], v[126:129], v[18:21]
	v_mfma_f32_16x16x32_bf16 v[166:169], v[114:117], v[126:129], v[102:105]
	v_mfma_f32_16x16x32_bf16 v[170:173], v[130:133], v[126:129], v[98:101]
	v_mfma_f32_16x16x32_bf16 v[174:177], v[142:145], v[126:129], v[94:97]
	s_nop 1
	v_add_u32_e32 v98, v186, v181
	ds_read_b128 v[186:189], v98 offset:32768
	ds_read_b128 v[94:97], v0 offset:12288
	s_waitcnt lgkmcnt(3)
	v_mfma_f32_16x16x32_bf16 v[14:17], v[106:109], v[146:149], v[14:17]
	v_mfma_f32_16x16x32_bf16 v[190:193], v[114:117], v[146:149], v[82:85]
	v_mfma_f32_16x16x32_bf16 v[194:197], v[130:133], v[146:149], v[78:81]
	v_mfma_f32_16x16x32_bf16 v[146:149], v[142:145], v[146:149], v[74:77]
	ds_read_b128 v[198:201], v98 offset:34816
	s_nop 1
	ds_read_b128 v[74:77], v0 offset:14336
	v_add_u32_e32 v0, v0, v181
	s_waitcnt lgkmcnt(4)
	v_mfma_f32_16x16x32_bf16 v[10:13], v[106:109], v[90:93], v[10:13]
	v_mfma_f32_16x16x32_bf16 v[202:205], v[114:117], v[90:93], v[66:69]
	v_mfma_f32_16x16x32_bf16 v[206:209], v[130:133], v[90:93], v[62:65]
	v_mfma_f32_16x16x32_bf16 v[226:229], v[142:145], v[90:93], v[58:61]
	ds_read_b128 v[230:233], v98 offset:36864
	s_nop 1
	ds_read_b128 v[58:61], v0 offset:0
	s_waitcnt lgkmcnt(4)
	v_mfma_f32_16x16x32_bf16 v[6:9], v[106:109], v[94:97], v[6:9]
	v_mfma_f32_16x16x32_bf16 v[234:237], v[114:117], v[94:97], v[50:53]
	v_mfma_f32_16x16x32_bf16 v[238:241], v[130:133], v[94:97], v[46:49]
	v_mfma_f32_16x16x32_bf16 v[242:245], v[142:145], v[94:97], v[42:45]
	ds_read_b128 v[246:249], v98 offset:38912
	s_nop 1
	ds_read_b128 v[42:45], v0 offset:2048
	s_waitcnt lgkmcnt(4)
	v_mfma_f32_16x16x32_bf16 v[2:5], v[106:109], v[74:77], v[2:5]
	v_mfma_f32_16x16x32_bf16 v[218:221], v[114:117], v[74:77], v[34:37]
	v_mfma_f32_16x16x32_bf16 v[130:133], v[130:133], v[74:77], v[38:41]
	v_mfma_f32_16x16x32_bf16 v[142:145], v[142:145], v[74:77], v[86:89]
	s_nop 0
	ds_read_b128 v[34:37], v0 offset:4096
	s_waitcnt lgkmcnt(3)
	v_mfma_f32_16x16x32_bf16 v[126:129], v[186:189], v[58:61], v[30:33]
	v_mfma_f32_16x16x32_bf16 v[122:125], v[198:201], v[58:61], v[110:113]
	v_mfma_f32_16x16x32_bf16 v[118:121], v[230:233], v[58:61], v[150:153]
	s_waitcnt lgkmcnt(2)
	v_mfma_f32_16x16x32_bf16 v[114:117], v[246:249], v[58:61], v[70:73]
	ds_read_b128 v[30:33], v0 offset:6144
	s_waitcnt lgkmcnt(2)
	v_mfma_f32_16x16x32_bf16 v[110:113], v[186:189], v[42:45], v[26:29]
	v_mfma_f32_16x16x32_bf16 v[106:109], v[198:201], v[42:45], v[138:141]
	v_mfma_f32_16x16x32_bf16 v[102:105], v[230:233], v[42:45], v[134:137]
	v_mfma_f32_16x16x32_bf16 v[98:101], v[246:249], v[42:45], v[54:57]
	ds_read_b128 v[26:29], v0 offset:8192
	s_waitcnt lgkmcnt(2)
	v_mfma_f32_16x16x32_bf16 v[94:97], v[186:189], v[34:37], v[22:25]
	v_mfma_f32_16x16x32_bf16 v[90:93], v[198:201], v[34:37], v[158:161]
	v_mfma_f32_16x16x32_bf16 v[86:89], v[230:233], v[34:37], v[162:165]
	v_mfma_f32_16x16x32_bf16 v[82:85], v[246:249], v[34:37], v[154:157]
	ds_read_b128 v[22:25], v0 offset:10240
	s_waitcnt lgkmcnt(2)
	v_mfma_f32_16x16x32_bf16 v[78:81], v[186:189], v[30:33], v[18:21]
	v_mfma_f32_16x16x32_bf16 v[74:77], v[198:201], v[30:33], v[166:169]
	v_mfma_f32_16x16x32_bf16 v[70:73], v[230:233], v[30:33], v[170:173]
	v_mfma_f32_16x16x32_bf16 v[66:69], v[246:249], v[30:33], v[174:177]
	ds_read_b128 v[18:21], v0 offset:12288
	s_waitcnt lgkmcnt(2)
	v_mfma_f32_16x16x32_bf16 v[62:65], v[186:189], v[26:29], v[14:17]
	v_mfma_f32_16x16x32_bf16 v[58:61], v[198:201], v[26:29], v[190:193]
	v_mfma_f32_16x16x32_bf16 v[54:57], v[230:233], v[26:29], v[194:197]
	v_mfma_f32_16x16x32_bf16 v[50:53], v[246:249], v[26:29], v[146:149]
	ds_read_b128 v[134:137], v0 offset:14336
	s_waitcnt lgkmcnt(0)
	s_barrier
	v_mfma_f32_16x16x32_bf16 v[46:49], v[186:189], v[22:25], v[10:13]
	v_mfma_f32_16x16x32_bf16 v[42:45], v[198:201], v[22:25], v[202:205]
	v_mfma_f32_16x16x32_bf16 v[38:41], v[230:233], v[22:25], v[206:209]
	v_mfma_f32_16x16x32_bf16 v[34:37], v[246:249], v[22:25], v[226:229]
	v_mfma_f32_16x16x32_bf16 v[30:33], v[186:189], v[18:21], v[6:9]
	v_mfma_f32_16x16x32_bf16 v[26:29], v[198:201], v[18:21], v[234:237]
	v_mfma_f32_16x16x32_bf16 v[22:25], v[230:233], v[18:21], v[238:241]
	v_mfma_f32_16x16x32_bf16 v[18:21], v[246:249], v[18:21], v[242:245]
	v_mfma_f32_16x16x32_bf16 v[14:17], v[186:189], v[134:137], v[2:5]
	v_mfma_f32_16x16x32_bf16 v[10:13], v[198:201], v[134:137], v[218:221]
	v_mfma_f32_16x16x32_bf16 v[2:5], v[230:233], v[134:137], v[130:133]
	v_mfma_f32_16x16x32_bf16 v[6:9], v[246:249], v[134:137], v[142:145]
	s_setprio 0
	s_cbranch_vccz .LBB0_900
	s_nop 0
	v_cvt_pk_bf16_f32 v130, v126, v127
	v_cvt_pk_bf16_f32 v131, v128, v129
	s_mov_b64 s[28:29], 0
